# k10: k9 + FFN-up epilogue second conv-weight load group issued with the first (one exposed round trip per unit removed)
# baseline (speedup 1.0000x reference)
; __device__ __forceinline__ float dpp_row_shr1(float x) { return __builtin_bit_cast(float, __builtin_amdgcn_update_dpp(__builtin_bit_cast(int, x), __builtin_bit_cast(int, x), 0x111, 0xf, 0xf, false)); }
;     __device__ __forceinline__ void operator()(f32x4 (&acc)[2][2][4][2], const pg8::Unit& u, int wr, int wc, int fr, int fq) const {
;     ...
;         for (int k = 0; k < 8; ++k) { const float rs = __builtin_amdgcn_rsqf(__hip_atomic_load(ssq + tok0 + k, __ATOMIC_RELAXED, __HIP_MEMORY_SCOPE_AGENT) * (1.0f / 1024.0f) + 1e-6f);
; #pragma unroll
;             for (int bj = 0; bj < 2; ++bj) { acc[k >> 2][bj][k & 3][0] = acc[k >> 2][bj][k & 3][0] * rs; acc[k >> 2][bj][k & 3][1] = acc[k >> 2][bj][k & 3][1] * rs; } }
;         const int grp = 2 * u.pm + wr;
;         const bool samp = (u.pm >= 64 && u.pm < PM_META), meta = (u.pm == PM_META);
;         const int sb = 32 * (u.pm - 64) + 16 * wr + fr;
;         const bool defer = (!samp && !meta && fr == 0);
;         const bool lastlane = meta ? (wr == 0 && fr == 1) : (!samp && fr == 15);
;         f32x4 w0[2], w1[2], w2[2], bb[2], p6[2], p7[2];
; #pragma unroll
;         for (int n = 0; n < 2; ++n) {
;             const int c4 = ch0 + 4 * n;
;             w0[n] = *(const f32x4*)(cw + c4); w1[n] = *(const f32x4*)(cw + DFF + c4); w2[n] = *(const f32x4*)(cw + 2 * DFF + c4); bb[n] = *(const f32x4*)(cb + c4);
; #pragma unroll
;             for (int e = 0; e < 4; ++e) { p6[n][e] = dpp_row_shr1(acc[1][0][2][n][e]); p7[n][e] = dpp_row_shr1(acc[1][0][3][n][e]); }
;             if (samp) { p6[n] = *(const f32x4*)(cst + (size_t)(sb * 2 + 0) * DFF + c4); p7[n] = *(const f32x4*)(cst + (size_t)(sb * 2 + 1) * DFF + c4); }
.LBB0_473:
	v_lshl_add_u32 v188, s96, 8, v231
	v_ashrrev_i32_e32 v189, 31, v188
	v_lshl_add_u64 v[4:5], v[188:189], 2, s[36:37]
	global_load_dword v239, v[4:5], off sc1
	global_load_dword v238, v[4:5], off offset:4 sc1
	global_load_dword v237, v[4:5], off offset:8 sc1
	global_load_dword v236, v[4:5], off offset:12 sc1
	global_load_dword v235, v[4:5], off offset:16 sc1
	global_load_dword v189, v[4:5], off offset:20 sc1
	global_load_dword v36, v[4:5], off offset:24 sc1
	global_load_dword v37, v[4:5], off offset:28 sc1
	v_lshl_or_b32 v196, s0, 7, v233
	v_ashrrev_i32_e32 v197, 31, v196
	v_lshlrev_b64 v[194:195], 2, v[196:197]
	v_lshl_add_u64 v[26:27], s[24:25], 0, v[194:195]
	v_lshl_add_u64 v[4:5], s[78:79], 0, v[194:195]
	v_lshl_add_u64 v[8:9], s[84:85], 0, v[194:195]
	v_lshl_add_u64 v[24:25], s[26:27], 0, v[194:195]
	global_load_dwordx4 v[12:15], v[26:27], off
	global_load_dwordx4 v[240:243], v[26:27], off offset:16
	global_load_dwordx4 v[244:247], v[4:5], off offset:16
	global_load_dwordx4 v[4:7], v[4:5], off
	global_load_dwordx4 v[168:171], v[8:9], off offset:16
	global_load_dwordx4 v[160:163], v[8:9], off
	global_load_dwordx4 v[164:167], v[24:25], off offset:16
	global_load_dwordx4 v[8:11], v[24:25], off
	s_and_b32 s10, s96, -4
	v_lshl_add_u32 v28, s96, 6, v232
	s_cmp_lg_u32 s10, 64
	v_mad_i64_i32 v[140:141], s[0:1], v28, s80, 0
	v_or_b32_e32 v28, 1, v28
	s_cselect_b64 s[0:1], -1, 0
	s_cmp_eq_u32 s10, 64
	v_mad_i64_i32 v[142:143], s[10:11], v28, s80, 0
	v_lshl_add_u64 v[28:29], s[28:29], 0, v[140:141]
	v_lshl_add_u64 v[198:199], v[28:29], 0, v[194:195]
	v_lshl_add_u64 v[30:31], s[28:29], 0, v[142:143]
	v_lshl_add_u64 v[200:201], v[30:31], 0, v[194:195]
	s_cselect_b64 s[46:47], -1, 0
	s_and_b64 vcc, exec, s[0:1]
	s_waitcnt vmcnt(0)
	v_fmamk_f32 v28, v36, 0x3a800000, v211
	v_rsq_f32_e32 v192, v28
	v_fmamk_f32 v28, v37, 0x3a800000, v211
	v_rsq_f32_e32 v190, v28
	v_pk_mul_f32 v[30:31], v[22:23], v[192:193] op_sel_hi:[1,0]
	v_pk_mul_f32 v[28:29], v[20:21], v[192:193] op_sel_hi:[1,0]
	v_pk_mul_f32 v[38:39], v[18:19], v[190:191] op_sel_hi:[1,0]
	v_pk_mul_f32 v[36:37], v[16:17], v[190:191] op_sel_hi:[1,0]
	v_mov_b32_e32 v176, v28
	v_mov_b32_e32 v172, v36
	v_mov_b32_e32 v177, v29
	v_mov_b32_e32 v173, v37
	v_mov_b32_e32 v178, v30
	v_mov_b32_e32 v174, v38
	v_mov_b32_e32 v179, v31
	v_mov_b32_e32 v175, v39
	v_mov_b32_dpp v176, v176 row_shr:1 row_mask:0xf bank_mask:0xf
	v_mov_b32_dpp v172, v172 row_shr:1 row_mask:0xf bank_mask:0xf
	v_mov_b32_dpp v177, v177 row_shr:1 row_mask:0xf bank_mask:0xf
	v_mov_b32_dpp v173, v173 row_shr:1 row_mask:0xf bank_mask:0xf
	v_mov_b32_dpp v178, v178 row_shr:1 row_mask:0xf bank_mask:0xf
	v_mov_b32_dpp v174, v174 row_shr:1 row_mask:0xf bank_mask:0xf
	v_mov_b32_dpp v179, v179 row_shr:1 row_mask:0xf bank_mask:0xf
	v_mov_b32_dpp v175, v175 row_shr:1 row_mask:0xf bank_mask:0xf
	s_cbranch_vccnz .LBB0_475
	global_load_dwordx4 v[176:179], v[198:199], off
	global_load_dwordx4 v[172:175], v[200:201], off

; __device__ __forceinline__ float dpp_row_shr1(float x) { return __builtin_bit_cast(float, __builtin_amdgcn_update_dpp(__builtin_bit_cast(int, x), __builtin_bit_cast(int, x), 0x111, 0xf, 0xf, false)); }
;     __device__ __forceinline__ void operator()(f32x4 (&acc)[2][2][4][2], const pg8::Unit& u, int wr, int wc, int fr, int fq) const {
;     ...
; #pragma unroll
;         for (int n = 0; n < 2; ++n) {
;             const int c4 = ch0 + 4 * n;
;             w0[n] = *(const f32x4*)(cw + c4); w1[n] = *(const f32x4*)(cw + DFF + c4); w2[n] = *(const f32x4*)(cw + 2 * DFF + c4); bb[n] = *(const f32x4*)(cb + c4);
; #pragma unroll
;             for (int e = 0; e < 4; ++e) { p6[n][e] = dpp_row_shr1(acc[1][0][2][n][e]); p7[n][e] = dpp_row_shr1(acc[1][0][3][n][e]); }
;             if (samp) { p6[n] = *(const f32x4*)(cst + (size_t)(sb * 2 + 0) * DFF + c4); p7[n] = *(const f32x4*)(cst + (size_t)(sb * 2 + 1) * DFF + c4); }
.LBB0_479:
	v_mov_b32_e32 v16, v240
	v_mov_b32_e32 v17, v241
	v_mov_b32_e32 v18, v242
	v_mov_b32_e32 v19, v243
	v_mov_b32_e32 v20, v244
	v_mov_b32_e32 v21, v245
	v_mov_b32_e32 v22, v246
	v_mov_b32_e32 v23, v247
	v_mov_b32_e32 v140, v168
	v_mov_b32_e32 v141, v169
	v_mov_b32_e32 v142, v170
	v_mov_b32_e32 v143, v171
	v_mov_b32_e32 v24, v164
	v_mov_b32_e32 v25, v165
	v_mov_b32_e32 v26, v166
	v_mov_b32_e32 v27, v167
	v_mov_b32_e32 v164, v192
	v_mov_b32_e32 v165, v192
	v_mov_b32_e32 v193, v192
	v_mov_b32_e32 v191, v190
	v_pk_mul_f32 v[34:35], v[34:35], v[164:165]
	v_mov_b32_e32 v164, v190
	v_mov_b32_e32 v165, v190
	v_pk_mul_f32 v[32:33], v[32:33], v[192:193]
	v_pk_mul_f32 v[42:43], v[42:43], v[164:165]
	v_pk_mul_f32 v[40:41], v[40:41], v[190:191]
	v_mov_b32_e32 v168, v32
	v_mov_b32_e32 v164, v40
	v_mov_b32_e32 v169, v33
	v_mov_b32_e32 v165, v41
	v_mov_b32_e32 v170, v34
	v_mov_b32_e32 v166, v42
	v_mov_b32_e32 v171, v35
	v_mov_b32_e32 v167, v43
	v_mov_b32_dpp v168, v168 row_shr:1 row_mask:0xf bank_mask:0xf
	v_mov_b32_dpp v164, v164 row_shr:1 row_mask:0xf bank_mask:0xf
	v_mov_b32_dpp v169, v169 row_shr:1 row_mask:0xf bank_mask:0xf
	v_mov_b32_dpp v165, v165 row_shr:1 row_mask:0xf bank_mask:0xf
	v_mov_b32_dpp v170, v170 row_shr:1 row_mask:0xf bank_mask:0xf
	v_mov_b32_dpp v166, v166 row_shr:1 row_mask:0xf bank_mask:0xf
	v_mov_b32_dpp v171, v171 row_shr:1 row_mask:0xf bank_mask:0xf
	s_and_b64 vcc, exec, s[12:13]
	v_mov_b32_dpp v167, v167 row_shr:1 row_mask:0xf bank_mask:0xf
	s_cbranch_vccnz .LBB0_498
	global_load_dwordx4 v[168:171], v[198:199], off offset:16
	global_load_dwordx4 v[164:167], v[200:201], off offset:16
	s_and_saveexec_b64 s[46:47], s[0:1]
	s_cbranch_execnz .LBB0_499
